# combined edits with the nt hint kept only on the in-proj epilogue stores (out rows stay cacheable for the next norm)
# baseline (speedup 1.0000x reference)
; #define MFMA32(a, b, c) __builtin_amdgcn_mfma_f32_32x32x16_bf16((a), (b), (c), 0, 0, 0)
; template <int EPI>
; DI void gemm_phase(const Params& p, char* lds, const bfu* __restrict__ A, const bfu* __restrict__ BT, int ntn, int l, const float* xin) {
;     ...
;       for (int s = 0; s < 4; ++s) {
;         if (s < 3) {
;           const unsigned co = (unsigned)((((s + 1) * 2 + h) ^ swz) << 4);
;           af[(s + 1) & 1][0] = *(const bf16x8*)(pa + co); af[(s + 1) & 1][1] = *(const bf16x8*)(pa + 4096 + co);
; #pragma unroll
;           for (int j = 0; j < 4; ++j) bfr[(s + 1) & 1][j] = *(const bf16x8*)(pb + j * 4096 + co);
;         }
;         SBAR();
; #pragma unroll
;         for (int i = 0; i < 2; ++i)
; #pragma unroll
;           for (int j = 0; j < 4; ++j) {
;             acc[i][j] = MFMA32(bfr[s & 1][j], af[s & 1][i], acc[i][j]);
;             if (s < 2 && (j & 1) && dnext) DMA_PIECE(dA, dB, dk, dso, s * 4 + i * 2 + (j >> 1));
;           }
;         SBAR();
;     ...
;       char* stg = lds + 65536 + wave * 8704;
;       const float* gate = (const float*)(p.ws + WS_MOD) + l * 6144 + (m0 >> 14) * 3072 + 2048;
;       float4 xn[8];
;     ...
;       LOADX(0);
; #pragma unroll
;       for (int ps = 0; ps < 4; ++ps) {
;         const int i = ps >> 1, jp = ps & 1;
;         float4 xc[8];
; #pragma unroll
;         for (int it = 0; it < 8; ++it) xc[it] = xn[it];
;         if (ps + 1 < 4) LOADX(ps + 1);
;         if (ps) WSYNC();
; #pragma unroll
;         for (int j2 = 0; j2 < 2; ++j2)
; #pragma unroll
;           for (int g = 0; g < 4; ++g) {
;             const f32x16& a = acc[i][2 * jp + j2];
;             float4 o; o.x = a[4 * g]; o.y = a[4 * g + 1]; o.z = a[4 * g + 2]; o.w = a[4 * g + 3];
;             *(float4*)(stg + r * 272 + (j2 * 32 + 8 * g + 4 * h) * 4) = o;
;           }
;         WSYNC();
; #pragma unroll
;         for (int it = 0; it < 8; ++it) {
;           const int id = it * 64 + lane, row = id >> 4, c = id & 15;
;           const float4 y = *(const float4*)(stg + row * 272 + c * 16);
;           const int m = m0 + wm * 64 + i * 32 + row, n = n0 + wn * 128 + jp * 64 + c * 4;
;           const float4 xv = xc[it];
;           const float4 gv = *(const float4*)(gate + n);
;           float4 o; o.x = xv.x + gv.x * y.x; o.y = xv.y + gv.y * y.y; o.z = xv.z + gv.z * y.z; o.w = xv.w + gv.w * y.w;
;           *(float4*)(p.out + (size_t)m * 1024 + n) = o;
.LBB0_801:
	v_add_u32_e32 v132, v209, v200
	v_add_u32_e32 v148, v210, v200
	ds_read_b128 v[128:131], v132
	ds_read_b128 v[132:135], v132 offset:4096
	ds_read_b128 v[136:139], v148 offset:32768
	ds_read_b128 v[140:143], v148 offset:36864
	ds_read_b128 v[144:147], v148 offset:40960
	ds_read_b128 v[148:151], v148 offset:45056
	s_waitcnt lgkmcnt(9)
	v_mfma_f32_32x32x16_bf16 v[112:127], v[172:175], v[164:167], v[112:127]
	s_waitcnt lgkmcnt(8)
	v_mfma_f32_32x32x16_bf16 v[96:111], v[168:171], v[164:167], v[96:111]
	s_waitcnt lgkmcnt(7)
	v_mfma_f32_32x32x16_bf16 v[80:95], v[160:163], v[164:167], v[80:95]
	s_waitcnt lgkmcnt(6)
	v_mfma_f32_32x32x16_bf16 v[64:79], v[156:159], v[164:167], v[64:79]
	v_mfma_f32_32x32x16_bf16 v[48:63], v[172:175], v[152:155], v[48:63]
	v_mfma_f32_32x32x16_bf16 v[32:47], v[168:171], v[152:155], v[32:47]
	v_mfma_f32_32x32x16_bf16 v[16:31], v[160:163], v[152:155], v[16:31]
	v_mfma_f32_32x32x16_bf16 v[0:15], v[156:159], v[152:155], v[0:15]
	s_waitcnt lgkmcnt(3)
	v_mfma_f32_32x32x16_bf16 v[112:127], v[136:139], v[128:131], v[112:127]
	s_waitcnt lgkmcnt(2)
	v_mfma_f32_32x32x16_bf16 v[96:111], v[140:143], v[128:131], v[96:111]
	s_waitcnt lgkmcnt(1)
	v_mfma_f32_32x32x16_bf16 v[80:95], v[144:147], v[128:131], v[80:95]
	s_waitcnt lgkmcnt(0)
	v_mfma_f32_32x32x16_bf16 v[64:79], v[148:151], v[128:131], v[64:79]
	v_mfma_f32_32x32x16_bf16 v[48:63], v[136:139], v[132:135], v[48:63]
	v_mfma_f32_32x32x16_bf16 v[32:47], v[140:143], v[132:135], v[32:47]
	v_mfma_f32_32x32x16_bf16 v[16:31], v[144:147], v[132:135], v[16:31]
	v_mfma_f32_32x32x16_bf16 v[0:15], v[148:151], v[132:135], v[0:15]
	s_lshr_b32 s4, s35, 6
	s_mulk_i32 s4, 0xc00
	s_ashr_i32 s5, s4, 31
	s_lshl_b64 s[4:5], s[4:5], 2
	s_add_u32 s4, s49, s4
	s_addc_u32 s5, s50, s5
	s_add_i32 s10, s10, s51
	v_or_b32_e32 v128, s10, v201
	v_ashrrev_i32_e32 v129, 31, v128
	v_lshlrev_b64 v[162:163], 12, v[128:129]
	v_or_b32_e32 v128, s10, v202
	v_ashrrev_i32_e32 v129, 31, v128
	v_lshlrev_b64 v[174:175], 12, v[128:129]
	v_or_b32_e32 v128, s10, v203
	v_ashrrev_i32_e32 v129, 31, v128
	v_lshlrev_b64 v[188:189], 12, v[128:129]
	v_or_b32_e32 v128, s10, v204
	v_or_b32_e32 v134, s10, v207
	v_ashrrev_i32_e32 v129, 31, v128
	v_ashrrev_i32_e32 v135, 31, v134
	v_lshlrev_b64 v[150:151], 12, v[128:129]
	v_or_b32_e32 v128, s10, v205
	v_or_b32_e32 v130, s10, v206
	v_lshlrev_b64 v[140:141], 12, v[134:135]
	v_or_b32_e32 v134, s10, v208
	s_waitcnt vmcnt(0) lgkmcnt(0)
	s_barrier
	v_ashrrev_i32_e32 v129, 31, v128
	v_ashrrev_i32_e32 v131, 31, v130
	v_ashrrev_i32_e32 v135, 31, v134
	ds_write_b128 v211, v[112:115]
	ds_write_b128 v211, v[116:119] offset:32
	ds_write_b128 v211, v[120:123] offset:64
	ds_write_b128 v211, v[124:127] offset:96
	ds_write_b128 v211, v[96:99] offset:128
	ds_write_b128 v211, v[100:103] offset:160
	ds_write_b128 v211, v[104:107] offset:192
	ds_write_b128 v211, v[108:111] offset:224
	v_or_b32_e32 v100, s8, v192
	v_lshl_add_u64 v[132:133], s[8:9], 2, v[178:179]
	v_lshlrev_b64 v[148:149], 12, v[128:129]
	v_lshlrev_b64 v[142:143], 12, v[130:131]
	v_lshlrev_b64 v[134:135], 12, v[134:135]
	s_add_u32 s4, s4, 0x26c2000
	v_ashrrev_i32_e32 v101, 31, v100
	v_lshl_add_u64 v[152:153], v[132:133], 0, v[174:175]
	v_lshl_add_u64 v[144:145], v[132:133], 0, v[188:189]
	v_lshl_add_u64 v[136:137], v[132:133], 0, v[150:151]
	v_lshl_add_u64 v[128:129], v[132:133], 0, v[148:149]
	v_lshl_add_u64 v[130:131], v[132:133], 0, v[142:143]
	v_lshl_add_u64 v[138:139], v[132:133], 0, v[140:141]
	v_lshl_add_u64 v[146:147], v[132:133], 0, v[134:135]
	s_addc_u32 s5, s5, 0
	v_lshlrev_b64 v[102:103], 2, v[100:101]
	v_lshl_add_u64 v[164:165], v[132:133], 0, v[162:163]
	v_lshl_add_u64 v[160:161], s[4:5], 0, v[102:103]
	global_load_dwordx4 v[96:99], v[146:147], off offset:256
	global_load_dwordx4 v[108:111], v[146:147], off
	global_load_dwordx4 v[104:107], v[138:139], off offset:256
	global_load_dwordx4 v[116:119], v[138:139], off
	global_load_dwordx4 v[112:115], v[130:131], off offset:256
	global_load_dwordx4 v[124:127], v[130:131], off
	global_load_dwordx4 v[120:123], v[128:129], off offset:256
	global_load_dwordx4 v[156:159], v[128:129], off
	s_nop 0
	global_load_dwordx4 v[128:131], v[136:137], off offset:256
	global_load_dwordx4 v[166:169], v[136:137], off
	s_nop 0
	global_load_dwordx4 v[136:139], v[144:145], off offset:256
	global_load_dwordx4 v[170:173], v[144:145], off
	s_nop 0
	global_load_dwordx4 v[144:147], v[152:153], off offset:256
	global_load_dwordx4 v[184:187], v[152:153], off
	s_nop 0
	global_load_dwordx4 v[152:155], v[164:165], off offset:256
	global_load_dwordx4 v[214:217], v[164:165], off
	s_waitcnt lgkmcnt(0)
	global_load_dwordx4 v[218:221], v[160:161], off
	v_lshlrev_b32_e32 v246, 5, v199
	v_add_u32_e32 v246, 0x22080, v246
	ds_read_b128 v[222:225], v212
	ds_read_b128 v[226:229], v212 offset:1088
	v_lshl_add_u64 v[164:165], s[28:29], 0, v[102:103]
	v_lshl_add_u64 v[230:231], v[164:165], 0, v[162:163]
	s_or_b32 s8, s10, 32
	v_or_b32_e32 v100, 64, v100
	v_or_b32_e32 v102, s8, v201
	v_ashrrev_i32_e32 v101, 31, v100
	v_ashrrev_i32_e32 v103, 31, v102
	v_lshl_add_u64 v[162:163], v[100:101], 2, s[4:5]
	v_readlane_b32 s4, v255, 10
	s_add_i32 s66, s66, s4
	s_and_b64 vcc, exec, s[6:7]
	s_waitcnt vmcnt(0) lgkmcnt(1)
	ds_write_b128 v246, v[218:221]
	v_pk_fma_f32 v[214:215], v[222:223], v[218:219], v[214:215]
	v_pk_fma_f32 v[216:217], v[224:225], v[220:221], v[216:217]
	global_store_dwordx4 v[230:231], v[214:217], off
	s_nop 0
	ds_read_b128 v[214:217], v246
	v_lshl_add_u64 v[222:223], v[164:165], 0, v[174:175]
	v_lshl_add_u64 v[224:225], v[164:165], 0, v[188:189]
	v_lshlrev_b64 v[188:189], 12, v[102:103]
	ds_read_b128 v[218:221], v212 offset:3264
	s_waitcnt lgkmcnt(1)
; #define WSYNC() asm volatile("s_waitcnt lgkmcnt(0)" ::: "memory")
; #define LOADX(ps_) do { _Pragma("unroll") for (int it = 0; it < 8; ++it) { const int id = it * 64 + lane, row = id >> 4, c = id & 15; \
;           xn[it] = *(const float4*)(xin + (size_t)(m0 + wm * 64 + ((ps_) >> 1) * 32 + row) * 1024 + n0 + wn * 128 + ((ps_) & 1) * 64 + c * 4); } } while (0)
; template <int EPI>
; DI void gemm_phase(const Params& p, char* lds, const bfu* __restrict__ A, const bfu* __restrict__ BT, int ntn, int l, const float* xin) {
;     ...
;       for (int ps = 0; ps < 4; ++ps) {
;         const int i = ps >> 1, jp = ps & 1;
;         float4 xc[8];
; #pragma unroll
;         for (int it = 0; it < 8; ++it) xc[it] = xn[it];
;         if (ps + 1 < 4) LOADX(ps + 1);
;         if (ps) WSYNC();
; #pragma unroll
;         for (int j2 = 0; j2 < 2; ++j2)
; #pragma unroll
;           for (int g = 0; g < 4; ++g) {
;             const f32x16& a = acc[i][2 * jp + j2];
;             float4 o; o.x = a[4 * g]; o.y = a[4 * g + 1]; o.z = a[4 * g + 2]; o.w = a[4 * g + 3];
;             *(float4*)(stg + r * 272 + (j2 * 32 + 8 * g + 4 * h) * 4) = o;
;           }
;         WSYNC();
; #pragma unroll
;         for (int it = 0; it < 8; ++it) {
;           const int id = it * 64 + lane, row = id >> 4, c = id & 15;
;           const float4 y = *(const float4*)(stg + row * 272 + c * 16);
;           const int m = m0 + wm * 64 + i * 32 + row, n = n0 + wn * 128 + jp * 64 + c * 4;
;           const float4 xv = xc[it];
;           const float4 gv = *(const float4*)(gate + n);
;           float4 o; o.x = xv.x + gv.x * y.x; o.y = xv.y + gv.y * y.y; o.z = xv.z + gv.z * y.z; o.w = xv.w + gv.w * y.w;
;           *(float4*)(p.out + (size_t)m * 1024 + n) = o;
;         }
	v_pk_fma_f32 v[184:185], v[226:227], v[214:215], v[184:185]
	v_pk_fma_f32 v[186:187], v[228:229], v[216:217], v[186:187]
	global_store_dwordx4 v[222:223], v[184:187], off
	s_nop 0
	ds_read_b128 v[184:187], v246
	ds_read_b128 v[214:217], v212 offset:2176
	v_lshl_add_u64 v[226:227], v[164:165], 0, v[134:135]
	v_lshl_add_u64 v[228:229], v[132:133], 0, v[188:189]
	s_waitcnt lgkmcnt(0)
	v_pk_fma_f32 v[170:171], v[214:215], v[184:185], v[170:171]
	v_pk_fma_f32 v[172:173], v[216:217], v[186:187], v[172:173]
	global_store_dwordx4 v[224:225], v[170:173], off
	s_nop 0
	ds_read_b128 v[170:173], v246
	v_lshl_add_u64 v[214:215], v[164:165], 0, v[150:151]
	v_lshl_add_u64 v[216:217], v[164:165], 0, v[148:149]
	ds_read_b128 v[148:151], v212 offset:5440
	s_waitcnt lgkmcnt(1)
	v_pk_fma_f32 v[166:167], v[218:219], v[170:171], v[166:167]
	v_pk_fma_f32 v[168:169], v[220:221], v[172:173], v[168:169]
	global_store_dwordx4 v[214:215], v[166:169], off
	s_nop 0
	ds_read_b128 v[166:169], v246
	ds_read_b128 v[170:173], v212 offset:4352
	v_lshl_add_u64 v[218:219], v[164:165], 0, v[142:143]
	v_lshl_add_u64 v[220:221], v[164:165], 0, v[140:141]
	ds_read_b128 v[140:143], v212 offset:7616
	s_waitcnt lgkmcnt(1)
	v_pk_fma_f32 v[156:157], v[170:171], v[166:167], v[156:157]
	v_pk_fma_f32 v[158:159], v[172:173], v[168:169], v[158:159]
	global_store_dwordx4 v[216:217], v[156:159], off
	s_nop 0
	ds_read_b128 v[156:159], v246
	v_or_b32_e32 v166, s8, v208
	v_ashrrev_i32_e32 v167, 31, v166
	v_lshlrev_b64 v[166:167], 12, v[166:167]
	v_lshl_add_u64 v[236:237], v[132:133], 0, v[166:167]
	s_waitcnt lgkmcnt(0)
	v_pk_fma_f32 v[124:125], v[148:149], v[156:157], v[124:125]
	v_pk_fma_f32 v[126:127], v[150:151], v[158:159], v[126:127]
	global_store_dwordx4 v[218:219], v[124:127], off
	s_nop 0
	ds_read_b128 v[124:127], v246
	ds_read_b128 v[148:151], v212 offset:6528
	v_or_b32_e32 v156, s8, v206
	v_or_b32_e32 v158, s8, v207
	v_ashrrev_i32_e32 v157, 31, v156
	v_ashrrev_i32_e32 v159, 31, v158
	v_lshlrev_b64 v[170:171], 12, v[156:157]
	v_lshlrev_b64 v[168:169], 12, v[158:159]
	v_lshl_add_u64 v[250:251], v[132:133], 0, v[170:171]
	v_lshl_add_u64 v[252:253], v[132:133], 0, v[168:169]
	s_waitcnt lgkmcnt(0)
	v_pk_fma_f32 v[116:117], v[148:149], v[124:125], v[116:117]
	v_pk_fma_f32 v[118:119], v[150:151], v[126:127], v[118:119]
	global_store_dwordx4 v[220:221], v[116:119], off
	s_nop 0
	ds_read_b128 v[116:119], v246
	v_or_b32_e32 v124, s8, v202
	v_or_b32_e32 v126, s8, v203
	v_or_b32_e32 v148, s8, v204
	v_or_b32_e32 v150, s8, v205
	v_ashrrev_i32_e32 v125, 31, v124
	v_ashrrev_i32_e32 v127, 31, v126
	v_ashrrev_i32_e32 v149, 31, v148
	v_ashrrev_i32_e32 v151, 31, v150
	v_lshlrev_b64 v[186:187], 12, v[124:125]
	v_lshlrev_b64 v[184:185], 12, v[126:127]
	v_lshlrev_b64 v[174:175], 12, v[148:149]
	v_lshlrev_b64 v[172:173], 12, v[150:151]
	v_lshl_add_u64 v[232:233], v[132:133], 0, v[186:187]
	v_lshl_add_u64 v[240:241], v[132:133], 0, v[184:185]
	v_lshl_add_u64 v[242:243], v[132:133], 0, v[174:175]
	v_lshl_add_u64 v[248:249], v[132:133], 0, v[172:173]
	s_waitcnt lgkmcnt(0)
	v_pk_fma_f32 v[100:101], v[140:141], v[116:117], v[108:109]
	v_pk_fma_f32 v[102:103], v[142:143], v[118:119], v[110:111]
	global_store_dwordx4 v[226:227], v[100:103], off
	global_load_dwordx4 v[100:103], v[236:237], off
	s_nop 0
	global_load_dwordx4 v[108:111], v[252:253], off
	global_load_dwordx4 v[116:119], v[250:251], off
	global_load_dwordx4 v[124:127], v[248:249], off
	global_load_dwordx4 v[132:135], v[242:243], off
	global_load_dwordx4 v[140:143], v[240:241], off
	global_load_dwordx4 v[148:151], v[232:233], off
	global_load_dwordx4 v[156:159], v[228:229], off
	s_waitcnt lgkmcnt(0)
	ds_write_b128 v211, v[80:83]
	ds_write_b128 v211, v[84:87] offset:32
	ds_write_b128 v211, v[88:91] offset:64
	ds_write_b128 v211, v[92:95] offset:96
	ds_write_b128 v211, v[64:67] offset:128
	ds_write_b128 v211, v[68:71] offset:160
	ds_write_b128 v211, v[72:75] offset:192
	ds_write_b128 v211, v[76:79] offset:224
	s_waitcnt lgkmcnt(0)
	global_load_dwordx4 v[64:67], v[162:163], off
	ds_read_b128 v[68:71], v212
	ds_read_b128 v[72:75], v212 offset:1088
	s_waitcnt vmcnt(0) lgkmcnt(1)
	ds_write_b128 v246, v[64:67] offset:16
	v_pk_fma_f32 v[64:65], v[68:69], v[64:65], v[152:153]
	v_pk_fma_f32 v[66:67], v[70:71], v[66:67], v[154:155]
	global_store_dwordx4 v[230:231], v[64:67], off offset:256
	s_nop 0
	ds_read_b128 v[64:67], v246 offset:16
	s_waitcnt lgkmcnt(0)
	v_pk_fma_f32 v[64:65], v[72:73], v[64:65], v[144:145]
	v_pk_fma_f32 v[66:67], v[74:75], v[66:67], v[146:147]
	global_store_dwordx4 v[222:223], v[64:67], off offset:256
	s_nop 0
	ds_read_b128 v[64:67], v246 offset:16
	ds_read_b128 v[68:71], v212 offset:2176
	ds_read_b128 v[72:75], v212 offset:3264
	s_waitcnt lgkmcnt(1)
	v_pk_fma_f32 v[64:65], v[68:69], v[64:65], v[136:137]
	v_pk_fma_f32 v[66:67], v[70:71], v[66:67], v[138:139]
	global_store_dwordx4 v[224:225], v[64:67], off offset:256
	s_nop 0
	ds_read_b128 v[64:67], v246 offset:16
	s_waitcnt lgkmcnt(0)
	v_pk_fma_f32 v[64:65], v[72:73], v[64:65], v[128:129]
	v_pk_fma_f32 v[66:67], v[74:75], v[66:67], v[130:131]
	global_store_dwordx4 v[214:215], v[64:67], off offset:256
	s_nop 0
	ds_read_b128 v[64:67], v246 offset:16
	ds_read_b128 v[68:71], v212 offset:4352
	ds_read_b128 v[72:75], v212 offset:5440
	s_waitcnt lgkmcnt(1)
	v_pk_fma_f32 v[64:65], v[68:69], v[64:65], v[120:121]
	v_pk_fma_f32 v[66:67], v[70:71], v[66:67], v[122:123]
	global_store_dwordx4 v[216:217], v[64:67], off offset:256
	s_nop 0
	ds_read_b128 v[64:67], v246 offset:16
	s_waitcnt lgkmcnt(0)
; #define WSYNC() asm volatile("s_waitcnt lgkmcnt(0)" ::: "memory")
; #define LOADX(ps_) do { _Pragma("unroll") for (int it = 0; it < 8; ++it) { const int id = it * 64 + lane, row = id >> 4, c = id & 15; \
;           xn[it] = *(const float4*)(xin + (size_t)(m0 + wm * 64 + ((ps_) >> 1) * 32 + row) * 1024 + n0 + wn * 128 + ((ps_) & 1) * 64 + c * 4); } } while (0)
; template <int EPI>
; DI void gemm_phase(const Params& p, char* lds, const bfu* __restrict__ A, const bfu* __restrict__ BT, int ntn, int l, const float* xin) {
;     ...
;       for (int ps = 0; ps < 4; ++ps) {
;         const int i = ps >> 1, jp = ps & 1;
;         float4 xc[8];
; #pragma unroll
;         for (int it = 0; it < 8; ++it) xc[it] = xn[it];
;         if (ps + 1 < 4) LOADX(ps + 1);
;         if (ps) WSYNC();
; #pragma unroll
;         for (int j2 = 0; j2 < 2; ++j2)
; #pragma unroll
;           for (int g = 0; g < 4; ++g) {
;             const f32x16& a = acc[i][2 * jp + j2];
;             float4 o; o.x = a[4 * g]; o.y = a[4 * g + 1]; o.z = a[4 * g + 2]; o.w = a[4 * g + 3];
;             *(float4*)(stg + r * 272 + (j2 * 32 + 8 * g + 4 * h) * 4) = o;
;           }
;         WSYNC();
; #pragma unroll
;         for (int it = 0; it < 8; ++it) {
;           const int id = it * 64 + lane, row = id >> 4, c = id & 15;
;           const float4 y = *(const float4*)(stg + row * 272 + c * 16);
;           const int m = m0 + wm * 64 + i * 32 + row, n = n0 + wn * 128 + jp * 64 + c * 4;
;           const float4 xv = xc[it];
;           const float4 gv = *(const float4*)(gate + n);
;           float4 o; o.x = xv.x + gv.x * y.x; o.y = xv.y + gv.y * y.y; o.z = xv.z + gv.z * y.z; o.w = xv.w + gv.w * y.w;
;           *(float4*)(p.out + (size_t)m * 1024 + n) = o;
;         }
	v_pk_fma_f32 v[64:65], v[72:73], v[64:65], v[112:113]
	v_pk_fma_f32 v[66:67], v[74:75], v[66:67], v[114:115]
	global_store_dwordx4 v[218:219], v[64:67], off offset:256
	s_nop 0
	ds_read_b128 v[64:67], v246 offset:16
	ds_read_b128 v[68:71], v212 offset:6528
	ds_read_b128 v[72:75], v212 offset:7616
	s_waitcnt lgkmcnt(1)
	v_pk_fma_f32 v[64:65], v[68:69], v[64:65], v[104:105]
	v_pk_fma_f32 v[66:67], v[70:71], v[66:67], v[106:107]
	global_store_dwordx4 v[220:221], v[64:67], off offset:256
	s_nop 0
	ds_read_b128 v[64:67], v246 offset:16
	s_waitcnt lgkmcnt(0)
	v_pk_fma_f32 v[64:65], v[72:73], v[64:65], v[96:97]
	v_pk_fma_f32 v[66:67], v[74:75], v[66:67], v[98:99]
	global_store_dwordx4 v[226:227], v[64:67], off offset:256
	global_load_dwordx4 v[64:67], v[236:237], off offset:256
	s_nop 0
	global_load_dwordx4 v[68:71], v[252:253], off offset:256
	global_load_dwordx4 v[72:75], v[250:251], off offset:256
	global_load_dwordx4 v[76:79], v[248:249], off offset:256
	global_load_dwordx4 v[80:83], v[242:243], off offset:256
	global_load_dwordx4 v[84:87], v[240:241], off offset:256
	global_load_dwordx4 v[88:91], v[232:233], off offset:256
	global_load_dwordx4 v[92:95], v[228:229], off offset:256
	s_waitcnt lgkmcnt(0)
	ds_write_b128 v211, v[48:51]
	ds_write_b128 v211, v[52:55] offset:32
	ds_write_b128 v211, v[56:59] offset:64
	ds_write_b128 v211, v[60:63] offset:96
	ds_write_b128 v211, v[32:35] offset:128
	ds_write_b128 v211, v[36:39] offset:160
	ds_write_b128 v211, v[40:43] offset:192
	ds_write_b128 v211, v[44:47] offset:224
	s_waitcnt lgkmcnt(0)
	s_nop 0
	ds_read_b128 v[32:35], v246
	ds_read_b128 v[36:39], v212
	ds_read_b128 v[40:43], v212 offset:1088
	v_lshl_add_u64 v[44:45], v[164:165], 0, v[188:189]
	v_lshl_add_u64 v[46:47], v[164:165], 0, v[186:187]
	v_lshl_add_u64 v[48:49], v[164:165], 0, v[184:185]
	v_lshl_add_u64 v[50:51], v[164:165], 0, v[174:175]
	v_lshl_add_u64 v[52:53], v[164:165], 0, v[172:173]
	v_lshl_add_u64 v[54:55], v[164:165], 0, v[170:171]
	v_lshl_add_u64 v[56:57], v[164:165], 0, v[168:169]
	s_waitcnt vmcnt(0) lgkmcnt(1)
	v_pk_fma_f32 v[32:33], v[36:37], v[32:33], v[156:157]
	v_pk_fma_f32 v[34:35], v[38:39], v[34:35], v[158:159]
	global_store_dwordx4 v[44:45], v[32:35], off
	s_nop 0
	ds_read_b128 v[32:35], v246
	ds_read_b128 v[36:39], v212 offset:2176
	s_waitcnt lgkmcnt(1)
	v_pk_fma_f32 v[32:33], v[40:41], v[32:33], v[148:149]
	v_pk_fma_f32 v[34:35], v[42:43], v[34:35], v[150:151]
	global_store_dwordx4 v[46:47], v[32:35], off
	s_nop 0
	ds_read_b128 v[32:35], v246
	ds_read_b128 v[40:43], v212 offset:3264
	s_waitcnt lgkmcnt(1)
	v_pk_fma_f32 v[32:33], v[36:37], v[32:33], v[140:141]
	v_pk_fma_f32 v[34:35], v[38:39], v[34:35], v[142:143]
	global_store_dwordx4 v[48:49], v[32:35], off
	s_nop 0
	ds_read_b128 v[32:35], v246
	ds_read_b128 v[36:39], v212 offset:4352
	s_waitcnt lgkmcnt(1)
	v_pk_fma_f32 v[32:33], v[40:41], v[32:33], v[132:133]
	v_pk_fma_f32 v[34:35], v[42:43], v[34:35], v[134:135]
	global_store_dwordx4 v[50:51], v[32:35], off
	s_nop 0
	ds_read_b128 v[32:35], v246
	ds_read_b128 v[40:43], v212 offset:5440
	s_waitcnt lgkmcnt(1)
	v_pk_fma_f32 v[32:33], v[36:37], v[32:33], v[124:125]
	v_pk_fma_f32 v[34:35], v[38:39], v[34:35], v[126:127]
	global_store_dwordx4 v[52:53], v[32:35], off
	s_nop 0
	ds_read_b128 v[32:35], v246
	ds_read_b128 v[36:39], v212 offset:6528
	s_waitcnt lgkmcnt(1)
	v_pk_fma_f32 v[32:33], v[40:41], v[32:33], v[116:117]
	v_pk_fma_f32 v[34:35], v[42:43], v[34:35], v[118:119]
	global_store_dwordx4 v[54:55], v[32:35], off
	s_nop 0
	ds_read_b128 v[32:35], v246
	ds_read_b128 v[40:43], v212 offset:7616
	s_waitcnt lgkmcnt(1)
	v_pk_fma_f32 v[32:33], v[36:37], v[32:33], v[108:109]
	v_pk_fma_f32 v[34:35], v[38:39], v[34:35], v[110:111]
	global_store_dwordx4 v[56:57], v[32:35], off
	s_nop 0
	ds_read_b128 v[32:35], v246
	v_lshl_add_u64 v[36:37], v[164:165], 0, v[166:167]
	s_waitcnt lgkmcnt(0)
	v_pk_fma_f32 v[32:33], v[40:41], v[32:33], v[100:101]
	v_pk_fma_f32 v[34:35], v[42:43], v[34:35], v[102:103]
	global_store_dwordx4 v[36:37], v[32:35], off
	s_waitcnt lgkmcnt(0)
	ds_write_b128 v211, v[16:19]
	ds_write_b128 v211, v[20:23] offset:32
	ds_write_b128 v211, v[24:27] offset:64
	ds_write_b128 v211, v[28:31] offset:96
	ds_write_b128 v211, v[0:3] offset:128
	ds_write_b128 v211, v[4:7] offset:160
	ds_write_b128 v211, v[8:11] offset:192
	ds_write_b128 v211, v[12:15] offset:224
	s_waitcnt lgkmcnt(0)
	s_nop 0
	ds_read_b128 v[0:3], v246 offset:16
	ds_read_b128 v[4:7], v212
	ds_read_b128 v[8:11], v212 offset:1088
	s_waitcnt vmcnt(0) lgkmcnt(1)
	v_pk_fma_f32 v[0:1], v[4:5], v[0:1], v[92:93]
	v_pk_fma_f32 v[2:3], v[6:7], v[2:3], v[94:95]
	global_store_dwordx4 v[44:45], v[0:3], off offset:256
	s_nop 0
	ds_read_b128 v[0:3], v246 offset:16
	s_waitcnt lgkmcnt(0)
	v_pk_fma_f32 v[0:1], v[8:9], v[0:1], v[88:89]
	v_pk_fma_f32 v[2:3], v[10:11], v[2:3], v[90:91]
	global_store_dwordx4 v[46:47], v[0:3], off offset:256
	s_nop 0
	ds_read_b128 v[0:3], v246 offset:16
	ds_read_b128 v[4:7], v212 offset:2176
	ds_read_b128 v[8:11], v212 offset:3264
	s_waitcnt lgkmcnt(1)
	v_pk_fma_f32 v[0:1], v[4:5], v[0:1], v[84:85]
	v_pk_fma_f32 v[2:3], v[6:7], v[2:3], v[86:87]
	global_store_dwordx4 v[48:49], v[0:3], off offset:256
	s_nop 0
	ds_read_b128 v[0:3], v246 offset:16
	s_waitcnt lgkmcnt(0)
	v_pk_fma_f32 v[0:1], v[8:9], v[0:1], v[80:81]
	v_pk_fma_f32 v[2:3], v[10:11], v[2:3], v[82:83]
	global_store_dwordx4 v[50:51], v[0:3], off offset:256
	s_nop 0
	ds_read_b128 v[0:3], v246 offset:16
	ds_read_b128 v[4:7], v212 offset:4352
	ds_read_b128 v[8:11], v212 offset:5440
	s_waitcnt lgkmcnt(1)
	v_pk_fma_f32 v[0:1], v[4:5], v[0:1], v[76:77]
	v_pk_fma_f32 v[2:3], v[6:7], v[2:3], v[78:79]
	global_store_dwordx4 v[52:53], v[0:3], off offset:256
	s_nop 0
	ds_read_b128 v[0:3], v246 offset:16
	s_waitcnt lgkmcnt(0)
	v_pk_fma_f32 v[0:1], v[8:9], v[0:1], v[72:73]
	v_pk_fma_f32 v[2:3], v[10:11], v[2:3], v[74:75]
	global_store_dwordx4 v[54:55], v[0:3], off offset:256
	s_nop 0
	ds_read_b128 v[0:3], v246 offset:16
	ds_read_b128 v[4:7], v212 offset:6528
	ds_read_b128 v[8:11], v212 offset:7616
	s_waitcnt lgkmcnt(1)
	v_pk_fma_f32 v[0:1], v[4:5], v[0:1], v[68:69]
	v_pk_fma_f32 v[2:3], v[6:7], v[2:3], v[70:71]
	global_store_dwordx4 v[56:57], v[0:3], off offset:256
	s_nop 0
	ds_read_b128 v[0:3], v246 offset:16
	s_waitcnt lgkmcnt(0)
	v_pk_fma_f32 v[0:1], v[8:9], v[0:1], v[64:65]
	v_pk_fma_f32 v[2:3], v[10:11], v[2:3], v[66:67]
	global_store_dwordx4 v[36:37], v[0:3], off offset:256
	s_cbranch_vccnz .LBB0_822
